# v36 with the attention prefetch-pointer advance moved in front of the step barrier (off the post-barrier critical chain)
# speedup vs baseline: 1.0090x; 1.0032x over previous
.LBB0_790:
	s_barrier
	v_readfirstlane_b32 s100, v235
	s_nop 3
	s_mul_i32 s101, s100, s42
	s_sub_i32 s0, s42, 1
	s_sub_i32 s0, s0, s2
	s_bitcmp0_b32 s100, 0
	s_cselect_b32 s0, s2, s0
	s_add_i32 s101, s101, s0
	v_add_u32_e32 v235, 1, v235
	v_mov_b32_e32 v0, s101
	s_movk_i32 s0, 0x480
	s_mov_b64 s[8:9], -1
	v_cmp_gt_i32_e64 s[6:7], s0, v0
	s_and_saveexec_b64 s[68:69], s[6:7]
	s_cbranch_execz .LBB0_789
	v_ashrrev_i32_e32 v1, 31, v0
	v_lshrrev_b32_e32 v1, 25, v1
	v_add_u32_e32 v1, v0, v1
	v_ashrrev_i32_e32 v8, 7, v1
	v_and_b32_e32 v1, 0xffffff80, v1
	v_sub_u32_e32 v0, v0, v1
	v_mov_b32_e32 v1, 11
	v_lshrrev_b16_sdwa v1, v1, sext(v0) dst_sel:DWORD dst_unused:UNUSED_PAD src0_sel:DWORD src1_sel:BYTE_0
	v_and_b32_e32 v1, 15, v1
	v_add_u16_e32 v1, v0, v1
	v_sub_u32_e32 v9, 8, v8
	v_ashrrev_i16_sdwa v2, v198, sext(v1) dst_sel:DWORD dst_unused:UNUSED_PAD src0_sel:DWORD src1_sel:BYTE_0
	s_movk_i32 s0, 0x810
	v_and_b32_e32 v1, 0xf0, v1
	v_mul_hi_i32_i24_sdwa v135, sext(v2), s0 dst_sel:DWORD dst_unused:UNUSED_PAD src0_sel:WORD_0 src1_sel:DWORD
	v_mul_i32_i24_sdwa v134, sext(v2), s0 dst_sel:DWORD dst_unused:UNUSED_PAD src0_sel:WORD_0 src1_sel:DWORD
	v_mul_hi_i32_i24_e32 v3, 0x2040, v0
	v_mul_i32_i24_e32 v2, 0x2040, v0
	v_lshlrev_b32_e32 v10, 8, v9
	v_sub_u16_e32 v4, v0, v1
	v_lshl_add_u64 v[140:141], s[62:63], 0, v[2:3]
	v_add_u32_e32 v164, v10, v156
	v_mov_b32_e32 v2, 6
	v_lshlrev_b32_sdwa v138, v2, sext(v4) dst_sel:DWORD dst_unused:UNUSED_PAD src0_sel:DWORD src1_sel:BYTE_0
	v_max_i32_e32 v6, 0xf0, v164
	v_ashrrev_i32_e32 v139, 31, v138
	v_add_u32_e32 v172, 0xffffff10, v6
	v_lshlrev_b64 v[2:3], 1, v[138:139]
	v_lshl_add_u64 v[6:7], v[134:135], 0, v[172:173]
	v_lshl_add_u64 v[4:5], v[120:121], 0, v[2:3]
	v_lshlrev_b64 v[6:7], 12, v[6:7]
	v_lshl_add_u64 v[6:7], v[4:5], 0, v[6:7]
	v_or_b32_e32 v139, 16, v164
	global_load_dwordx4 v[20:23], v[6:7], off
	global_load_dwordx4 v[24:27], v[6:7], off offset:64
	v_max_i32_e32 v6, 0xf0, v139
	v_add_u32_e32 v172, 0xffffff10, v6
	v_lshl_add_u64 v[6:7], v[134:135], 0, v[172:173]
	v_lshlrev_b64 v[6:7], 12, v[6:7]
	v_ashrrev_i32_e32 v1, 31, v0
	v_lshl_add_u64 v[4:5], v[4:5], 0, v[6:7]
	global_load_dwordx4 v[28:31], v[4:5], off
	global_load_dwordx4 v[32:35], v[4:5], off offset:64
	v_lshl_add_u64 v[4:5], v[134:135], 0, v[124:125]
	v_lshlrev_b64 v[0:1], 6, v[0:1]
	v_lshlrev_b64 v[4:5], 11, v[4:5]
	v_lshl_add_u64 v[0:1], v[0:1], 0, v[122:123]
	v_mov_b64_e32 v[6:7], s[88:89]
	v_lshl_add_u64 v[4:5], s[70:71], 0, v[4:5]
	v_mad_u64_u32 v[144:145], s[6:7], v0, s52, v[6:7]
	v_lshl_add_u64 v[4:5], v[4:5], 0, v[2:3]
	v_lshlrev_b32_e32 v142, 1, v126
	v_mov_b32_e32 v143, v173
	v_mad_i32_i24 v145, v1, s52, v145
	v_mov_b32_e32 v131, v173
	v_lshlrev_b32_e32 v165, 2, v9
	v_lshl_add_u64 v[4:5], v[4:5], 0, v[142:143]
	v_lshl_add_u64 v[0:1], v[144:145], 0, v[130:131]
	v_mov_b32_e32 v133, v173
	v_or_b32_e32 v166, 3, v165
	global_load_dwordx4 v[36:39], v[4:5], off
	global_load_dwordx4 v[40:43], v[0:1], off offset:-96
	v_lshl_add_u64 v[0:1], v[140:141], 0, v[132:133]
	global_load_dword v131, v[0:1], off offset:-192
	v_min_u32_e32 v0, 4, v166
	v_lshl_add_u32 v6, v0, 6, v201
	v_add_u32_e32 v0, v6, v122
	v_max_i32_e32 v172, 0, v0
	v_lshl_add_u64 v[0:1], v[134:135], 0, v[172:173]
	v_lshlrev_b64 v[0:1], 11, v[0:1]
	v_lshl_add_u64 v[0:1], s[70:71], 0, v[0:1]
	v_add_u32_e32 v4, v6, v126
	v_lshl_add_u64 v[0:1], v[0:1], 0, v[2:3]
	v_max_i32_e32 v4, 0, v4
	v_lshl_add_u64 v[0:1], v[0:1], 0, v[142:143]
	v_lshlrev_b32_e32 v172, 1, v4
	v_lshl_add_u64 v[4:5], v[144:145], 0, v[172:173]
	global_load_dwordx4 v[44:47], v[0:1], off
	global_load_dwordx4 v[48:51], v[4:5], off
	v_add_u32_e32 v0, v6, v154
	v_max_i32_e32 v0, 0, v0
	v_lshlrev_b32_e32 v172, 2, v0
	v_lshl_add_u64 v[0:1], v[140:141], 0, v[172:173]
	global_load_dword v167, v[0:1], off
	v_min_u32_e32 v0, 5, v166
	v_lshl_add_u32 v6, v0, 6, v201
	v_add_u32_e32 v0, v6, v122
	v_max_i32_e32 v172, 0, v0
	v_lshl_add_u64 v[0:1], v[134:135], 0, v[172:173]
	v_lshlrev_b64 v[0:1], 11, v[0:1]
	v_lshl_add_u64 v[0:1], s[70:71], 0, v[0:1]
	v_add_u32_e32 v4, v6, v126
	v_lshl_add_u64 v[0:1], v[0:1], 0, v[2:3]
	v_max_i32_e32 v4, 0, v4
	v_lshl_add_u64 v[0:1], v[0:1], 0, v[142:143]
	v_lshlrev_b32_e32 v172, 1, v4
	v_lshl_add_u64 v[4:5], v[144:145], 0, v[172:173]
	global_load_dwordx4 v[52:55], v[0:1], off
	global_load_dwordx4 v[56:59], v[4:5], off
	v_add_u32_e32 v0, v6, v154
	v_max_i32_e32 v0, 0, v0
	v_lshlrev_b32_e32 v172, 2, v0
	v_lshl_add_u64 v[0:1], v[140:141], 0, v[172:173]
	global_load_dword v169, v[0:1], off
	v_sub_u32_e32 v0, 0, v8
	v_or_b32_e32 v1, v10, v155
	v_lshl_add_u64 v[146:147], v[128:129], 0, v[2:3]
	v_lshlrev_b32_e32 v0, 8, v0
	v_mov_b32_e32 v2, v173
	v_mov_b32_e32 v3, v173
	v_add_u32_e32 v133, s85, v1
	v_sub_u32_e32 v168, 0, v0
	v_mov_b32_e32 v172, v173
	v_mov_b32_e32 v0, v173
	v_mov_b32_e32 v1, v173
	v_mov_b64_e32 v[6:7], v[2:3]
	v_mov_b64_e32 v[10:11], v[2:3]
	v_mov_b64_e32 v[14:15], v[2:3]
	v_mov_b64_e32 v[18:19], v[2:3]
	v_mov_b64_e32 v[62:63], v[2:3]
	v_mov_b64_e32 v[66:67], v[2:3]
	v_mov_b64_e32 v[70:71], v[2:3]
	s_mov_b32 s60, s87
	s_mov_b32 s84, 0
	v_or_b32_e32 v143, 16, v133
	v_mov_b32_e32 v148, 0xff800000
	s_mov_b64 s[34:35], 0
	v_mov_b32_e32 v170, 0
	s_mov_b32 s87, 0
	v_mov_b64_e32 v[4:5], v[0:1]
	v_mov_b64_e32 v[8:9], v[0:1]
	v_mov_b64_e32 v[12:13], v[0:1]
	v_mov_b64_e32 v[16:17], v[0:1]
	v_mov_b64_e32 v[60:61], v[0:1]
	v_mov_b64_e32 v[64:65], v[0:1]
	v_mov_b64_e32 v[68:69], v[0:1]
	v_mov_b64_e32 v[136:137], v[172:173]
	v_mov_b32_e32 v149, 0xff800000
	v_min_u32_e32 v228, 5, v166
	v_lshl_add_u32 v234, v228, 6, v201
	v_add_u32_e32 v228, v234, v122
	v_add_u32_e32 v230, v234, v126
	v_max_i32_e32 v172, 0, v228
	v_max_i32_e32 v230, 0, v230
	v_lshl_add_u64 v[228:229], v[134:135], 0, v[172:173]
	v_lshlrev_b32_e32 v172, 1, v230
	v_add_u32_e32 v234, v234, v154
	v_lshlrev_b64 v[228:229], 11, v[228:229]
	v_lshl_add_u64 v[230:231], v[144:145], 0, v[172:173]
	v_max_i32_e32 v172, 0, v234
	v_lshl_add_u64 v[228:229], v[146:147], 0, v[228:229]
	v_lshl_add_u64 v[232:233], v[172:173], 2, v[140:141]
	v_mov_b32_e32 v172, v173
	s_branch .LBB0_798

.LBB0_800:
	s_or_b64 exec, exec, s[6:7]
	v_readfirstlane_b32 s100, v166
	s_add_i32 s101, s87, 5
	s_cmp_lt_u32 s101, s100
	s_cselect_b32 s100, 0x20000, 0
	s_mov_b32 s101, 0
	v_lshl_add_u64 v[228:229], s[100:101], 0, v[228:229]
	s_lshr_b32 s100, s100, 10
	v_lshl_add_u64 v[230:231], s[100:101], 0, v[230:231]
	s_lshl_b32 s100, s100, 1
	v_lshl_add_u64 v[232:233], s[100:101], 0, v[232:233]
	s_waitcnt lgkmcnt(0)
	s_barrier
	global_load_dwordx4 v[36:39], v[228:229], off
	s_nop 0
	global_load_dwordx4 v[40:43], v[230:231], off
	s_add_i32 s0, s87, 3
	global_load_dword v131, v[232:233], off
	s_cmp_eq_u32 s87, 0
	s_cselect_b64 s[10:11], -1, 0
	v_cmp_ge_u32_e64 s[6:7], s0, v165
	v_cmp_lt_u32_e64 s[8:9], s0, v165
	s_or_b64 s[10:11], s[10:11], s[6:7]
	s_and_saveexec_b64 s[12:13], s[10:11]
	s_xor_b64 s[56:57], exec, s[12:13]
	s_cbranch_execz .LBB0_806
	s_and_saveexec_b64 s[10:11], s[6:7]
	v_add_u32_e32 v73, s84, v168
	v_add_u32_e32 v73, 0xfffff8c0, v73
	v_cmp_ge_i32_e64 s[6:7], s93, v73
	s_andn2_b64 s[8:9], s[8:9], exec
	s_and_b64 s[6:7], s[6:7], exec
	s_or_b64 s[8:9], s[8:9], s[6:7]
	s_or_b64 exec, exec, s[10:11]
	s_and_saveexec_b64 s[64:65], s[8:9]
	s_cbranch_execz .LBB0_805
	s_cmp_eq_u32 s87, 0
	s_cbranch_scc1 .Lattn_band1
	s_add_i32 s101, s87, 3
	v_readfirstlane_b32 s100, v165
	s_sub_i32 s100, s101, s100
	s_lshl_b32 s100, s100, 6
	s_add_i32 s100, s100, 63
	v_readfirstlane_b32 s101, v192
	s_lshr_b32 s101, s101, 6
	s_lshl_b32 s101, s101, 5
	s_cmp_le_i32 s100, s101
	s_cbranch_scc0 .Lattn_band1
	s_mov_b64 s[6:7], exec
	s_branch .Lattn_nb1

.LBB0_811:
	s_or_b64 exec, exec, s[6:7]
	v_readfirstlane_b32 s100, v166
	s_add_i32 s101, s87, 6
	s_cmp_lt_u32 s101, s100
	s_cselect_b32 s100, 0x20000, 0
	s_mov_b32 s101, 0
	v_lshl_add_u64 v[228:229], s[100:101], 0, v[228:229]
	s_lshr_b32 s100, s100, 10
	v_lshl_add_u64 v[230:231], s[100:101], 0, v[230:231]
	s_lshl_b32 s100, s100, 1
	v_lshl_add_u64 v[232:233], s[100:101], 0, v[232:233]
	s_waitcnt lgkmcnt(0)
	s_barrier
	global_load_dwordx4 v[44:47], v[228:229], off
	s_nop 0
	global_load_dwordx4 v[48:51], v[230:231], off
	s_add_i32 s6, s87, 4
	global_load_dword v167, v[232:233], off
	v_cmp_ge_u32_e64 s[6:7], s6, v165
	s_and_saveexec_b64 s[8:9], s[6:7]
	s_xor_b64 s[64:65], exec, s[8:9]
	s_cbranch_execz .LBB0_815
	v_add_u32_e32 v73, s84, v168
	v_add_u32_e32 v73, 0xfffff900, v73
	v_cmp_ge_i32_e64 s[6:7], s93, v73
	s_and_saveexec_b64 s[72:73], s[6:7]
	s_cbranch_execz .LBB0_814
	s_add_i32 s101, s87, 4
	v_readfirstlane_b32 s100, v165
	s_sub_i32 s100, s101, s100
	s_lshl_b32 s100, s100, 6
	s_add_i32 s100, s100, 63
	v_readfirstlane_b32 s101, v192
	s_lshr_b32 s101, s101, 6
	s_lshl_b32 s101, s101, 5
	s_cmp_le_i32 s100, s101
	s_cbranch_scc0 .Lattn_band2
	s_mov_b64 s[6:7], exec
	s_branch .Lattn_nb2

.LBB0_821:
	s_or_b64 exec, exec, s[6:7]
	v_readfirstlane_b32 s100, v166
	s_add_i32 s101, s87, 7
	s_cmp_lt_u32 s101, s100
	s_cselect_b32 s100, 0x20000, 0
	s_mov_b32 s101, 0
	v_lshl_add_u64 v[228:229], s[100:101], 0, v[228:229]
	s_lshr_b32 s100, s100, 10
	v_lshl_add_u64 v[230:231], s[100:101], 0, v[230:231]
	s_lshl_b32 s100, s100, 1
	v_lshl_add_u64 v[232:233], s[100:101], 0, v[232:233]
	s_waitcnt lgkmcnt(0)
	s_barrier
	global_load_dwordx4 v[52:55], v[228:229], off
	s_nop 0
	global_load_dwordx4 v[56:59], v[230:231], off
	v_cmp_ge_u32_e64 s[6:7], s8, v165
	global_load_dword v169, v[232:233], off
	s_and_saveexec_b64 s[8:9], s[6:7]
	s_xor_b64 s[64:65], exec, s[8:9]
	s_cbranch_execz .LBB0_825
	v_add_u32_e32 v73, s84, v168
	v_add_u32_e32 v73, 0xfffff940, v73
	v_cmp_ge_i32_e64 s[6:7], s93, v73
	s_and_saveexec_b64 s[72:73], s[6:7]
	s_cbranch_execz .LBB0_824
	s_add_i32 s101, s87, 5
	v_readfirstlane_b32 s100, v165
	s_sub_i32 s100, s101, s100
	s_lshl_b32 s100, s100, 6
	s_add_i32 s100, s100, 63
	v_readfirstlane_b32 s101, v192
	s_lshr_b32 s101, s101, 6
	s_lshl_b32 s101, s101, 5
	s_cmp_le_i32 s100, s101
	s_cbranch_scc0 .Lattn_band3
	s_mov_b64 s[6:7], exec
	s_branch .Lattn_nb3
